# P3: QA fragments carried in registers from att stream to next step o stream; o tile pieces paired with v_permlane16_swap into one dwordx4 store per step
# speedup vs baseline: 1.0278x; 1.0097x over previous
.LBB0_349:
	s_lshr_b32 s34, s16, 6
	s_and_b64 s[18:19], exec, s[38:39]
	s_cselect_b32 s7, 0, 0x4000000
	s_add_u32 s7, s24, s7
	s_addc_u32 s9, s25, 0
	s_ashr_i32 s11, s10, 31
	s_lshl_b64 s[18:19], s[10:11], 20
	s_add_u32 s43, s7, s18
	s_addc_u32 s63, s9, s19
	s_and_b64 s[44:45], exec, s[38:39]
	s_cselect_b32 s7, s59, 0x6000000
	s_add_u32 s7, s24, s7
	s_addc_u32 s9, s25, 0
	s_add_u32 s64, s7, s18
	s_addc_u32 s65, s9, s19
	s_lshl_b64 s[14:15], s[14:15], 1
	s_add_u32 s46, s51, s14
	s_addc_u32 s47, s52, s15
	s_lshl_b32 s7, s10, 7
	s_lshl_b32 s9, s17, 6
	s_or_b32 s10, s7, s9
	s_ashr_i32 s11, s10, 31
	s_lshl_b64 s[10:11], s[10:11], 10
	s_ashr_i32 s31, s30, 31
	s_add_u32 s48, s33, s10
	s_addc_u32 s49, s50, s11
	s_lshr_b32 s18, s16, 7
	s_lshl_b64 s[10:11], s[30:31], 7
	s_bfe_u32 s31, s16, 0x20006
	s_and_b32 s66, s18, 0x1fffffe
	s_lshl_b32 s7, s12, 13
	s_lshl_b32 s9, s12, 14
	s_add_u32 s14, s43, s9
	s_addc_u32 s15, s63, 0
	v_lshl_add_u64 v[0:1], s[14:15], 0, v[120:121]
	s_add_u32 s16, s64, s9
	v_add_co_u32_e32 v0, vcc, s60, v0
	s_addc_u32 s17, s65, 0
	s_nop 0
	v_addc_co_u32_e32 v1, vcc, 0, v1, vcc
	v_lshl_add_u64 v[2:3], s[16:17], 0, v[120:121]
	v_add_co_u32_e32 v2, vcc, s60, v2
	global_load_dwordx4 v[56:59], v120, s[14:15]
	global_load_dwordx4 v[60:63], v120, s[16:17]
	v_addc_co_u32_e32 v3, vcc, 0, v3, vcc
	global_load_dwordx4 v[64:67], v[0:1], off
	global_load_dwordx4 v[68:71], v[2:3], off
	s_add_u32 s14, s46, s7
	s_addc_u32 s15, s47, 0
	global_load_dwordx4 v[72:75], v120, s[14:15]
	s_lshl_b32 s7, s12, 10
	s_add_u32 s12, s48, s7
	s_addc_u32 s13, s49, 0
	global_load_dwordx4 v[76:79], v142, s[12:13]
	global_load_dwordx4 v[0:3], v[126:127], off
	global_load_dwordx4 v[4:7], v[126:127], off offset:16
	global_load_dwordx4 v[8:11], v[128:129], off
	global_load_dwordx4 v[12:15], v[128:129], off offset:16
	global_load_dwordx4 v[16:19], v[130:131], off
	global_load_dwordx4 v[20:23], v[130:131], off offset:16
	global_load_dwordx4 v[24:27], v[132:133], off
	global_load_dwordx4 v[28:31], v[132:133], off offset:16
	s_waitcnt vmcnt(34)
	v_add_u32_e32 v32, 0, v154
	v_or_b32_e32 v144, s10, v122
	v_mov_b32_e32 v33, v121
	s_waitcnt vmcnt(20)
	v_add_u32_e32 v82, 0x1e400, v32
	v_and_b32_e32 v32, 0xf87, v144
	v_cmp_ne_u64_e32 vcc, 0, v[32:33]
	s_lshl_b32 s7, s8, 13
	s_lshl_b32 s9, s8, 14
	v_cndmask_b32_e64 v32, 0, 1, vcc
	s_add_u32 s10, s43, s9
	v_mov_b32_e32 v145, s11
	v_mov_b32_e32 v34, s11
	v_sub_co_u32_e32 v80, vcc, v144, v32
	s_addc_u32 s11, s63, 0
	s_nop 0
	v_subbrev_co_u32_e32 v81, vcc, 0, v34, vcc
	v_lshl_add_u64 v[36:37], s[10:11], 0, v[120:121]
	global_load_dwordx4 v[32:35], v120, s[10:11]
	s_add_u32 s10, s64, s9
	v_add_co_u32_e32 v36, vcc, s60, v36
	s_addc_u32 s11, s65, 0
	s_nop 0
	v_addc_co_u32_e32 v37, vcc, 0, v37, vcc
	v_lshl_add_u64 v[38:39], s[10:11], 0, v[120:121]
	s_add_u32 s12, s46, s7
	v_add_co_u32_e32 v40, vcc, s60, v38
	s_addc_u32 s13, s47, 0
	s_lshl_b32 s7, s8, 10
	v_addc_co_u32_e32 v41, vcc, 0, v39, vcc
	s_add_u32 s8, s48, s7
	global_load_dwordx4 v[36:39], v[36:37], off
	s_nop 0
	global_load_dwordx4 v[44:47], v[40:41], off
	s_nop 0
	global_load_dwordx4 v[40:43], v120, s[10:11]
	global_load_dwordx4 v[48:51], v120, s[12:13]
	s_addc_u32 s9, s49, 0
	s_lshl_b32 s7, s6, 13
	s_lshl_b32 s10, s6, 14
	global_load_dwordx4 v[52:55], v142, s[8:9]
	s_add_u32 s8, s43, s10
	s_addc_u32 s9, s63, 0
	s_add_u32 s10, s64, s10
	s_addc_u32 s11, s65, 0
	s_mul_i32 s67, s31, 0x1100
	v_add_u32_e32 v170, s67, v155
	v_lshl_or_b32 v173, s66, 4, v123
	v_mul_lo_u32 v174, v173, s3
	s_mov_b32 s44, 0
	s_mov_b32 s45, s44
	v_mov_b32_e32 v143, v121
	v_lshl_add_u32 v178, s34, 5, v160
	v_add_u32_e32 v181, 0xf000, v178
	v_add_u32_e32 v183, s67, v157
	s_waitcnt vmcnt(19)
	ds_write_b128 v168, v[56:59]
	s_waitcnt vmcnt(17)
	ds_write_b128 v168, v[64:67] offset:8704
	ds_write_b128 v168, v[60:63] offset:17408
	s_waitcnt vmcnt(16)
	ds_write_b128 v168, v[68:71] offset:26112
	s_waitcnt vmcnt(15)
	ds_write_b128 v169, v[72:75] offset:34816
	s_waitcnt vmcnt(14)
	ds_write_b128 v82, v[76:79]
	v_lshlrev_b64 v[56:57], 11, v[80:81]
	v_lshlrev_b64 v[64:65], 11, v[144:145]
	v_lshl_add_u64 v[72:73], s[8:9], 0, v[120:121]
	v_lshl_add_u64 v[56:57], v[134:135], 0, v[56:57]
	v_lshl_add_u64 v[66:67], v[134:135], 0, v[64:65]
	v_lshl_add_u64 v[68:69], v[136:137], 0, v[64:65]
	v_add_co_u32_e32 v80, vcc, s60, v72
	global_load_dwordx4 v[56:59], v[56:57], off
	s_nop 0
	global_load_dwordx4 v[60:63], v[66:67], off
	s_nop 0
	global_load_dwordx4 v[64:67], v[66:67], off offset:2048
	s_nop 0
	global_load_dwordx4 v[68:71], v[68:69], off
	v_addc_co_u32_e32 v81, vcc, 0, v73, vcc
	global_load_dwordx4 v[72:75], v120, s[8:9]
	global_load_dwordx4 v[76:79], v120, s[10:11]
	s_add_u32 s8, s46, s7
	v_lshl_add_u64 v[82:83], s[10:11], 0, v[120:121]
	s_addc_u32 s9, s47, 0
	s_lshl_b32 s6, s6, 10
	v_add_co_u32_e32 v84, vcc, s60, v82
	s_add_u32 s6, s48, s6
	s_nop 0
	v_addc_co_u32_e32 v85, vcc, 0, v83, vcc
	s_addc_u32 s7, s49, 0
	global_load_dwordx4 v[80:83], v[80:81], off
	s_nop 0
	global_load_dwordx4 v[84:87], v[84:85], off
	s_lshl_b32 s12, s18, 4
	global_load_dwordx4 v[88:91], v120, s[8:9]
	global_load_dwordx4 v[92:95], v142, s[6:7]
	s_waitcnt lgkmcnt(0)
	s_barrier
	ds_read_b128 v[96:99], v170 offset:17408
	s_mul_i32 s6, s66, 0x1100
	v_add_u32_e32 v171, s6, v155
	ds_read_b128 v[100:103], v171
	s_or_b32 s68, s12, 16
	ds_read_b128 v[104:107], v170 offset:17472
	ds_read_b128 v[108:111], v171 offset:64
	s_mul_i32 s6, s68, 0x110
	s_waitcnt lgkmcnt(2)
	v_mfma_f32_16x16x32_bf16 v[100:103], v[96:99], v[100:103], 0
	v_add_u32_e32 v172, s6, v155
	ds_read_b128 v[112:115], v172
	ds_read_b128 v[116:119], v172 offset:64
	v_or_b32_e32 v179, s68, v123
	s_waitcnt lgkmcnt(2)
	v_mfma_f32_16x16x32_bf16 v[100:103], v[104:107], v[108:111], v[100:103]
	ds_read_b128 v[108:111], v170 offset:17536
	v_mov_b32_e32 v184, v165
	v_mov_b64_e32 v[152:153], v[140:141]
	s_waitcnt lgkmcnt(2)
	v_mfma_f32_16x16x32_bf16 v[96:99], v[96:99], v[112:115], 0
	s_waitcnt lgkmcnt(1)
	v_mfma_f32_16x16x32_bf16 v[96:99], v[104:107], v[116:119], v[96:99]
	ds_read_b128 v[104:107], v171 offset:128
	ds_read_b128 v[112:115], v170 offset:17600
	ds_read_b128 v[116:119], v171 offset:192
	s_waitcnt lgkmcnt(2)
	v_mfma_f32_16x16x32_bf16 v[100:103], v[108:111], v[104:107], v[100:103]
	ds_read_b128 v[104:107], v172 offset:128
	ds_read_b128 v[146:149], v172 offset:192
	s_waitcnt lgkmcnt(1)
	v_mfma_f32_16x16x32_bf16 v[96:99], v[108:111], v[104:107], v[96:99]
	v_lshl_or_b32 v104, s31, 4, v124
	v_or_b32_e32 v107, 2, v104
	v_or_b32_e32 v108, 3, v104
	v_mfma_f32_16x16x32_bf16 v[100:103], v[112:115], v[116:119], v[100:103]
	v_cmp_gt_u32_e32 vcc, v104, v173
	v_cmp_ge_u32_e64 s[6:7], v104, v173
	v_cmp_gt_u32_e64 s[8:9], v107, v173
	v_cmp_gt_u32_e64 s[10:11], v108, v173
	v_lshlrev_b32_e32 v105, 1, v104
	s_xor_b64 vcc, s[38:39], vcc
	s_xor_b64 s[6:7], s[38:39], s[6:7]
	s_xor_b64 s[8:9], s[38:39], s[8:9]
	s_xor_b64 s[10:11], s[38:39], s[10:11]
	v_add_u32_e32 v106, s57, v105
	v_cndmask_b32_e32 v100, 0, v100, vcc
	v_cndmask_b32_e64 v101, 0, v101, s[6:7]
	v_cndmask_b32_e64 v102, 0, v102, s[8:9]
	v_cndmask_b32_e64 v103, 0, v103, s[10:11]
	s_waitcnt lgkmcnt(0)
	v_mfma_f32_16x16x32_bf16 v[96:99], v[112:115], v[146:149], v[96:99]
	v_cvt_pk_bf16_f32 v100, v100, v101
	v_cvt_pk_bf16_f32 v101, v102, v103
	v_add_u32_e32 v175, v106, v174
	ds_write_b64 v175, v[100:101]
	v_or_b32_e32 v100, s12, v164
	v_cmp_gt_u32_e64 s[12:13], v104, v100
	v_cmp_ge_u32_e64 s[14:15], v104, v100
	v_cmp_gt_u32_e64 s[16:17], v107, v100
	v_cmp_gt_u32_e64 s[18:19], v108, v100
	s_xor_b64 s[12:13], s[38:39], s[12:13]
	s_xor_b64 s[14:15], s[38:39], s[14:15]
	s_xor_b64 s[16:17], s[38:39], s[16:17]
	s_xor_b64 s[18:19], s[38:39], s[18:19]
	v_cndmask_b32_e64 v96, 0, v96, s[12:13]
	v_cndmask_b32_e64 v97, 0, v97, s[14:15]
	v_cndmask_b32_e64 v98, 0, v98, s[16:17]
	v_cndmask_b32_e64 v99, 0, v99, s[18:19]
	v_mul_lo_u32 v176, v100, s3
	v_cvt_pk_bf16_f32 v96, v96, v97
	v_cvt_pk_bf16_f32 v97, v98, v99
	v_add_u32_e32 v177, v106, v176
	ds_write_b64 v177, v[96:97]
	v_mov_b64_e32 v[96:97], s[44:45]
	global_store_dwordx2 v[138:139], v[96:97], off
	global_store_dwordx2 v[138:139], v[96:97], off
	global_store_dwordx2 v[138:139], v[96:97], off
	global_store_dwordx2 v[138:139], v[96:97], off
	global_store_dwordx2 v[138:139], v[96:97], off
	s_lshl_b32 s31, s31, 5
	global_store_dwordx2 v[138:139], v[96:97], off
	v_lshl_or_b32 v96, s34, 4, v124
	s_add_u32 s20, s20, s31
	s_waitcnt lgkmcnt(0)
	v_lshl_add_u64 v[148:149], s[48:49], 0, v[142:143]
	v_lshlrev_b32_e32 v143, 2, v96
	v_lshlrev_b32_e32 v98, 1, v96
	s_addc_u32 s21, s21, 0
	v_lshlrev_b32_e32 v96, 1, v124
	v_mov_b32_e32 v97, v121
	v_lshl_add_u64 v[150:151], s[20:21], 0, v[96:97]
	v_mov_b32_e32 v100, 0
	v_mov_b32_e32 v96, 1.0
	v_lshl_add_u64 v[146:147], s[46:47], 0, v[120:121]
	s_mul_i32 s45, s66, 0x900
	s_mul_i32 s46, s68, 0x90
	v_add_u32_e32 v180, s58, v105
	s_mov_b32 s47, 62
	v_add_u32_e32 v182, v163, v98
	v_mov_b32_e32 v97, v96
	v_mov_b32_e32 v98, v96
	v_mov_b32_e32 v99, v96
	v_mov_b32_e32 v101, v100
	v_mov_b32_e32 v102, v100
	v_mov_b32_e32 v103, v100
	v_mov_b32_e32 v104, v100
	v_mov_b32_e32 v105, v100
	v_mov_b32_e32 v106, v100
	v_mov_b32_e32 v107, v100
	v_mov_b32_e32 v108, v100
	v_mov_b32_e32 v109, v100
	v_mov_b32_e32 v110, v100
	v_mov_b32_e32 v111, v100
	v_mov_b32_e32 v112, v100
	v_mov_b32_e32 v113, v100
	v_mov_b32_e32 v114, v100
	v_mov_b32_e32 v115, v100
	v_mov_b32_e32 v138, v154
	v_mov_b32_e32 v164, v175
	v_mov_b32_e32 v180, v177
	v_add_u32_e32 v142, s45, v156
	v_add_u32_e32 v159, s46, v156
	v_and_b32_e32 v240, 63, v158
	v_lshrrev_b32_e32 v241, 4, v240
	v_bfe_u32 v242, v240, 2, 2
	v_and_b32_e32 v243, 3, v240
	v_lshl_add_u32 v244, v241, 3, v242
	v_lshrrev_b32_e32 v245, 1, v242
	v_and_b32_e32 v246, 1, v241
	v_lshl_or_b32 v245, v246, 1, v245
	v_lshlrev_b32_e32 v244, 7, v244
	v_lshl_add_u32 v244, v243, 3, v244
	v_add_u32_e32 v244, 0x8800, v244
	v_xor_b32_e32 v246, 0, v245
	v_lshl_add_u32 v186, v246, 5, v244
	v_xor_b32_e32 v246, 1, v245
	v_lshl_add_u32 v187, v246, 5, v244
	v_xor_b32_e32 v246, 2, v245
	v_lshl_add_u32 v188, v246, 5, v244
	v_xor_b32_e32 v246, 3, v245
	v_lshl_add_u32 v189, v246, 5, v244
	s_lshr_b32 s77, s31, 5
	v_xor_b32_e32 v246, s77, v245
	v_lshl_add_u32 v139, v246, 5, v244
	ds_read_b128 v[122:125], v171
	ds_read_b128 v[126:129], v172
	ds_read_b128 v[130:133], v171 offset:64
	ds_read_b128 v[160:163], v172 offset:64
	ds_read_b128 v[210:213], v171 offset:128
	ds_read_b128 v[154:157], v172 offset:128
	ds_read_b128 v[206:209], v171 offset:192
	ds_read_b128 v[174:177], v172 offset:192
	s_waitcnt lgkmcnt(0)
	v_and_b32_e32 v240, 16, v158
	v_cmp_ne_u32_e64 s[20:21], 0, v240
	v_lshrrev_b32_e32 v240, 1, v240
	s_nop 1
	v_cndmask_b32_e64 v173, v173, v179, s[20:21]
	v_sub_co_u32_e64 v150, s[20:21], v150, v240
	s_nop 1
	v_subbrev_co_u32_e64 v151, s[20:21], 0, v151, s[20:21]
	v_readfirstlane_b32 s69, v158
	s_lshr_b32 s69, s69, 6
.LBB0_350:
	s_add_i32 s34, s47, 1
	s_and_b64 s[20:21], exec, s[38:39]
	s_cselect_b32 s48, s44, s34
	s_waitcnt vmcnt(18)
	ds_write_b128 v168, v[32:35] offset:44032
	s_waitcnt vmcnt(17)
	ds_write_b128 v168, v[36:39] offset:52736
	s_waitcnt vmcnt(16)
	ds_write_b128 v168, v[40:43] offset:61440
	s_waitcnt vmcnt(15)
	ds_write_b128 v166, v[44:47] offset:8704
	s_waitcnt vmcnt(14)
	ds_write_b128 v167, v[48:51]
	v_add_u32_e32 v32, s61, v138
	s_min_u32 s49, s44, 60
	s_waitcnt vmcnt(13)
	s_cmp_lg_u32 s69, 0
	s_cbranch_scc1 .Lev_skip_a
	ds_write_b128 v32, v[52:55]
.Lev_skip_a:
	s_add_i32 s34, s49, 3
	v_sub_u32_e64 v32, 60, s44 clamp
	s_and_b64 s[20:21], exec, s[38:39]
	v_readfirstlane_b32 s20, v32
	s_cselect_b32 s66, s34, s20
	s_lshl_b32 s34, s66, 13
	s_lshl_b32 s67, s66, 14
	s_add_u32 s20, s43, s67
	s_addc_u32 s21, s63, 0
	v_lshl_add_u64 v[36:37], s[20:21], 0, v[120:121]
	global_load_dwordx4 v[32:35], v120, s[20:21] nt
	v_add_co_u32_e64 v36, s[20:21], s60, v36
	v_lshl_add_u64 v[48:49], v[146:147], 0, s[34:35]
	s_nop 0
	v_addc_co_u32_e64 v37, s[20:21], 0, v37, s[20:21]
	s_add_u32 s20, s64, s67
	s_addc_u32 s21, s65, 0
	v_lshl_add_u64 v[44:45], s[20:21], 0, v[120:121]
	global_load_dwordx4 v[36:39], v[36:37], off nt
	s_lshl_b32 s34, s66, 10
	global_load_dwordx4 v[40:43], v120, s[20:21] nt
	v_add_co_u32_e64 v44, s[20:21], s60, v44
	v_lshl_add_u64 v[52:53], v[148:149], 0, s[34:35]
	s_nop 0
	v_addc_co_u32_e64 v45, s[20:21], 0, v45, s[20:21]
	s_lshl_b32 s20, s49, 1
	s_add_i32 s34, s20, 4
	s_waitcnt vmcnt(13)
	v_mov_b32_e32 v214, v64
	v_mov_b32_e32 v215, v65
	v_mov_b32_e32 v216, v66
	v_mov_b32_e32 v217, v67
	v_lshl_add_u64 v[64:65], v[144:145], 0, s[34:35]
	s_add_i32 s34, 0, 0x1e400
	v_mov_b32_e32 v198, v56
	v_mov_b32_e32 v199, v57
	v_mov_b32_e32 v200, v58
	v_mov_b32_e32 v201, v59
	v_mov_b32_e32 v202, v60
	v_mov_b32_e32 v203, v61
	v_mov_b32_e32 v204, v62
	v_mov_b32_e32 v205, v63
	s_waitcnt vmcnt(12)
	v_mov_b32_e32 v242, v68
	v_mov_b32_e32 v243, v69
	v_mov_b32_e32 v244, v70
	v_mov_b32_e32 v245, v71
	v_add_u32_e32 v116, s34, v143
	ds_read_b128 v[190:193], v116
	v_and_b32_e32 v66, 0xfff, v64
	v_cmp_ne_u32_e64 s[20:21], 0, v66
	v_add_u32_e32 v185, 0, v143
	v_add_u32_e32 v116, 0x1e600, v185
	s_waitcnt lgkmcnt(0)
	v_pk_mul_f32 v[192:193], v[98:99], v[192:193]
	v_pk_mul_f32 v[190:191], v[96:97], v[190:191]
	v_pk_mul_f32 v[98:99], v[102:103], v[192:193]
	v_pk_mul_f32 v[96:97], v[100:101], v[190:191]
	v_cndmask_b32_e64 v56, 0, 1, s[20:21]
	v_cvt_pk_bf16_f32 v100, v96, v97
	v_cvt_pk_bf16_f32 v101, v98, v99
	v_sub_co_u32_e64 v56, s[20:21], v64, v56
	ds_read_b128 v[116:119], v116
	ds_write_b64 v182, v[100:101]
	v_pk_mul_f32 v[100:101], v[104:105], v[190:191]
	v_pk_mul_f32 v[102:103], v[106:107], v[192:193]
	v_subbrev_co_u32_e64 v57, s[20:21], 0, v65, s[20:21]
	v_cvt_pk_bf16_f32 v104, v100, v101
	v_cvt_pk_bf16_f32 v105, v102, v103
	v_cmp_ne_u32_e64 s[20:21], s62, v66
	ds_write_b64 v182, v[104:105] offset:4352
	v_pk_mul_f32 v[104:105], v[108:109], v[190:191]
	v_pk_mul_f32 v[106:107], v[110:111], v[192:193]
	v_cndmask_b32_e64 v66, 0, 1, s[20:21]
	v_mov_b32_e32 v67, s35
	v_cvt_pk_bf16_f32 v108, v104, v105
	v_cvt_pk_bf16_f32 v109, v106, v107
	v_lshlrev_b64 v[68:69], 11, v[64:65]
	v_lshl_add_u64 v[64:65], v[64:65], 0, v[66:67]
	ds_write_b64 v182, v[108:109] offset:8704
	v_pk_mul_f32 v[108:109], v[112:113], v[190:191]
	v_pk_mul_f32 v[110:111], v[114:115], v[192:193]
	v_lshlrev_b64 v[56:57], 11, v[56:57]
	v_lshlrev_b64 v[64:65], 11, v[64:65]
	v_cvt_pk_bf16_f32 v112, v108, v109
	v_cvt_pk_bf16_f32 v113, v110, v111
	v_lshl_add_u64 v[56:57], v[134:135], 0, v[56:57]
	v_lshl_add_u64 v[60:61], v[134:135], 0, v[68:69]
	v_lshl_add_u64 v[64:65], v[134:135], 0, v[64:65]
	v_lshl_add_u64 v[68:69], v[136:137], 0, v[68:69]
	ds_write_b64 v182, v[112:113] offset:13056
	global_load_dwordx4 v[44:47], v[44:45], off nt
	global_load_dwordx4 v[48:51], v[48:49], off nt
	global_load_dwordx4 v[52:55], v[52:53], off
	global_load_dwordx4 v[56:59], v[56:57], off
	s_lshl_b32 s48, s48, 6
	global_load_dwordx4 v[60:63], v[60:61], off
	s_nop 0
	global_load_dwordx4 v[64:67], v[64:65], off
	s_nop 0
	global_load_dwordx4 v[68:71], v[68:69], off nt
	s_waitcnt lgkmcnt(0)
	s_barrier
	ds_read_b128 v[218:221], v183
	ds_read_b128 v[230:233], v183 offset:64
	v_and_b32_e32 v250, 0xfff, v184
	v_cmp_ne_u32_e64 s[20:21], 0, v250
	v_add_u32_e32 v184, 4, v184
	s_nop 0
	v_cndmask_b32_e64 v198, 0, v198, s[20:21]
	v_cndmask_b32_e64 v199, 0, v199, s[20:21]
	v_cndmask_b32_e64 v200, 0, v200, s[20:21]
	v_cndmask_b32_e64 v201, 0, v201, s[20:21]
	v_cmp_ne_u32_e64 s[20:21], s62, v250
	v_lshlrev_b32_e32 v246, 16, v202
	v_and_b32_e32 v247, 0xffff0000, v202
	v_cndmask_b32_e64 v214, 0, v214, s[20:21]
	v_cndmask_b32_e64 v215, 0, v215, s[20:21]
	v_cndmask_b32_e64 v216, 0, v216, s[20:21]
	v_cndmask_b32_e64 v217, 0, v217, s[20:21]
	v_pk_mul_f32 v[246:247], v[8:9], v[246:247]
	v_lshlrev_b32_e32 v248, 16, v198
	v_and_b32_e32 v249, 0xffff0000, v198
	v_pk_fma_f32 v[246:247], v[0:1], v[248:249], v[246:247]
	v_lshlrev_b32_e32 v248, 16, v214
	v_and_b32_e32 v249, 0xffff0000, v214
	v_pk_fma_f32 v[246:247], v[16:17], v[248:249], v[246:247]
	v_pk_add_f32 v[246:247], v[24:25], v[246:247]
	v_lshlrev_b32_e32 v248, 16, v242
	v_and_b32_e32 v249, 0xffff0000, v242
	v_pk_mul_f32 v[246:247], v[246:247], v[248:249]
	v_cvt_pk_bf16_f32 v198, v246, v247
	v_lshlrev_b32_e32 v246, 16, v203
	v_and_b32_e32 v247, 0xffff0000, v203
	v_pk_mul_f32 v[246:247], v[10:11], v[246:247]
	v_lshlrev_b32_e32 v248, 16, v199
	v_and_b32_e32 v249, 0xffff0000, v199
	v_pk_fma_f32 v[246:247], v[2:3], v[248:249], v[246:247]
	v_lshlrev_b32_e32 v248, 16, v215
	v_and_b32_e32 v249, 0xffff0000, v215
	v_pk_fma_f32 v[246:247], v[18:19], v[248:249], v[246:247]
	v_pk_add_f32 v[246:247], v[26:27], v[246:247]
	v_lshlrev_b32_e32 v248, 16, v243
	v_and_b32_e32 v249, 0xffff0000, v243
	v_pk_mul_f32 v[246:247], v[246:247], v[248:249]
	v_cvt_pk_bf16_f32 v199, v246, v247
	v_lshlrev_b32_e32 v246, 16, v204
	v_and_b32_e32 v247, 0xffff0000, v204
	v_pk_mul_f32 v[246:247], v[12:13], v[246:247]
	v_lshlrev_b32_e32 v248, 16, v200
	v_and_b32_e32 v249, 0xffff0000, v200
	v_pk_fma_f32 v[246:247], v[4:5], v[248:249], v[246:247]
	v_lshlrev_b32_e32 v248, 16, v216
	v_and_b32_e32 v249, 0xffff0000, v216
	v_pk_fma_f32 v[246:247], v[20:21], v[248:249], v[246:247]
	v_pk_add_f32 v[246:247], v[28:29], v[246:247]
	v_lshlrev_b32_e32 v248, 16, v244
	v_and_b32_e32 v249, 0xffff0000, v244
	v_pk_mul_f32 v[246:247], v[246:247], v[248:249]
	v_cvt_pk_bf16_f32 v200, v246, v247
	v_lshlrev_b32_e32 v246, 16, v205
	v_and_b32_e32 v247, 0xffff0000, v205
	v_pk_mul_f32 v[246:247], v[14:15], v[246:247]
	v_lshlrev_b32_e32 v248, 16, v201
	v_and_b32_e32 v249, 0xffff0000, v201
	v_pk_fma_f32 v[246:247], v[6:7], v[248:249], v[246:247]
	v_lshlrev_b32_e32 v248, 16, v217
	v_and_b32_e32 v249, 0xffff0000, v217
	v_pk_fma_f32 v[246:247], v[22:23], v[248:249], v[246:247]
	v_pk_add_f32 v[246:247], v[30:31], v[246:247]
	v_lshlrev_b32_e32 v248, 16, v245
	v_and_b32_e32 v249, 0xffff0000, v245
	v_pk_mul_f32 v[246:247], v[246:247], v[248:249]
	v_cvt_pk_bf16_f32 v201, v246, v247
	global_store_dwordx4 v[152:153], v[198:201], off
	s_nop 1
	ds_read_b128 v[242:245], v183 offset:128
	s_waitcnt lgkmcnt(2)
	v_mfma_f32_16x16x32_bf16 v[198:201], v[218:221], v[122:125], 0
	v_mfma_f32_16x16x32_bf16 v[202:205], v[218:221], v[126:129], 0
	ds_read_b128 v[218:221], v183 offset:192
	s_waitcnt lgkmcnt(2)
	v_mfma_f32_16x16x32_bf16 v[198:201], v[230:233], v[130:133], v[198:201]
	v_mfma_f32_16x16x32_bf16 v[202:205], v[230:233], v[160:163], v[202:205]
	ds_read_b128 v[230:233], v170 offset:61440
	ds_read_b128 v[122:125], v171 offset:44032
	ds_read_b128 v[126:129], v172 offset:44032
	s_waitcnt lgkmcnt(4)
	v_mfma_f32_16x16x32_bf16 v[198:201], v[242:245], v[210:213], v[198:201]
	v_mfma_f32_16x16x32_bf16 v[202:205], v[242:245], v[154:157], v[202:205]
	ds_read_b128 v[242:245], v170 offset:61504
	ds_read_b128 v[130:133], v171 offset:44096
	ds_read_b128 v[160:163], v172 offset:44096
	s_waitcnt lgkmcnt(6)
	v_mfma_f32_16x16x32_bf16 v[198:201], v[218:221], v[206:209], v[198:201]
	v_mfma_f32_16x16x32_bf16 v[202:205], v[218:221], v[174:177], v[202:205]
	ds_read_b128 v[218:221], v170 offset:61568
	ds_read_b128 v[210:213], v171 offset:44160
	ds_read_b128 v[154:157], v172 offset:44160
	s_waitcnt lgkmcnt(6)
	v_mfma_f32_16x16x32_bf16 v[190:193], v[230:233], v[122:125], 0
	v_mfma_f32_16x16x32_bf16 v[194:197], v[230:233], v[126:129], 0
	ds_read_b128 v[230:233], v170 offset:61632
	ds_read_b128 v[206:209], v171 offset:44224
	ds_read_b128 v[174:177], v172 offset:44224
	s_waitcnt lgkmcnt(6)
	v_mfma_f32_16x16x32_bf16 v[190:193], v[242:245], v[130:133], v[190:193]
	v_mfma_f32_16x16x32_bf16 v[194:197], v[242:245], v[160:163], v[194:197]
	ds_read_b64_tr_b16 v[242:243], v139
	ds_read_b64_tr_b16 v[244:245], v139 offset:512
	ds_read_b128 v[246:249], v142
	ds_read_b128 v[250:253], v159
	s_waitcnt lgkmcnt(7)
	v_mfma_f32_16x16x32_bf16 v[190:193], v[218:221], v[210:213], v[190:193]
	v_mfma_f32_16x16x32_bf16 v[194:197], v[218:221], v[154:157], v[194:197]
	ds_read_b64_tr_b16 v[218:219], v139 offset:4096
	ds_read_b64_tr_b16 v[220:221], v139 offset:4608
	ds_read_b128 v[222:225], v142 offset:64
	ds_read_b128 v[226:229], v159 offset:64
	s_waitcnt lgkmcnt(8)
	v_mfma_f32_16x16x32_bf16 v[190:193], v[230:233], v[206:209], v[190:193]
	v_mfma_f32_16x16x32_bf16 v[194:197], v[230:233], v[174:177], v[194:197]
	s_nop 6
	v_cndmask_b32_e32 v190, 0, v190, vcc
	v_cndmask_b32_e64 v191, 0, v191, s[6:7]
	v_cndmask_b32_e64 v192, 0, v192, s[8:9]
	v_cndmask_b32_e64 v193, 0, v193, s[10:11]
	v_cvt_pk_bf16_f32 v190, v190, v191
	v_cvt_pk_bf16_f32 v191, v192, v193
	v_cndmask_b32_e64 v194, 0, v194, s[12:13]
	v_cndmask_b32_e64 v195, 0, v195, s[14:15]
	v_cndmask_b32_e64 v196, 0, v196, s[16:17]
	v_cndmask_b32_e64 v197, 0, v197, s[18:19]
	v_cvt_pk_bf16_f32 v194, v194, v195
	v_cvt_pk_bf16_f32 v195, v196, v197
	ds_write_b64 v164, v[190:191] offset:9216
	ds_write_b64 v180, v[194:195] offset:9216
	ds_read_b64_tr_b16 v[190:191], v178 offset:17408
	ds_read_b64_tr_b16 v[192:193], v178 offset:18496
	ds_read_b64_tr_b16 v[194:195], v178 offset:26112
	ds_read_b64_tr_b16 v[196:197], v178 offset:27200
	s_waitcnt lgkmcnt(10)
	v_mfma_f32_16x16x32_bf16 v[198:201], v[242:245], v[246:249], v[198:201]
	v_mfma_f32_16x16x32_bf16 v[202:205], v[242:245], v[250:253], v[202:205]
	ds_read_b64_tr_b16 v[242:243], v186
	ds_read_b64_tr_b16 v[244:245], v186 offset:512
	ds_read_b64_tr_b16 v[246:247], v187
	ds_read_b64_tr_b16 v[248:249], v187 offset:512
	s_waitcnt lgkmcnt(10)
	v_mfma_f32_16x16x32_bf16 v[198:201], v[218:221], v[222:225], v[198:201]
	v_mfma_f32_16x16x32_bf16 v[202:205], v[218:221], v[226:229], v[202:205]
	ds_read_b64_tr_b16 v[218:219], v188
	ds_read_b64_tr_b16 v[220:221], v188 offset:512
	ds_read_b64_tr_b16 v[222:223], v189
	ds_read_b64_tr_b16 v[224:225], v189 offset:512
	s_waitcnt lgkmcnt(8)
	ds_read_b64_tr_b16 v[230:231], v186 offset:4096
	ds_read_b64_tr_b16 v[232:233], v186 offset:4608
	ds_read_b64_tr_b16 v[234:235], v187 offset:4096
	ds_read_b64_tr_b16 v[236:237], v187 offset:4608
	s_waitcnt lgkmcnt(8)
	v_mfma_f32_16x16x32_bf16 v[96:99], v[190:193], v[242:245], v[96:99]
	v_mfma_f32_16x16x32_bf16 v[100:103], v[190:193], v[246:249], v[100:103]
	ds_read_b64_tr_b16 v[242:243], v188 offset:4096
	ds_read_b64_tr_b16 v[244:245], v188 offset:4608
	ds_read_b64_tr_b16 v[246:247], v189 offset:4096
	ds_read_b64_tr_b16 v[248:249], v189 offset:4608
	v_cvt_pk_bf16_f32 v198, v198, v199
	v_cvt_pk_bf16_f32 v199, v200, v201
	v_cvt_pk_bf16_f32 v200, v202, v203
	v_cvt_pk_bf16_f32 v201, v204, v205
	v_add_u32_e32 v254, s48, v173
	v_mad_u64_u32 v[254:255], s[20:21], v254, s42, 0
	v_lshl_add_u64 v[254:255], v[254:255], 1, v[150:151]
	v_permlane16_swap_b32_e32 v198, v200
	v_permlane16_swap_b32_e32 v199, v201
	global_store_dwordx4 v[254:255], v[198:201], off
	s_waitcnt lgkmcnt(8)
	v_mfma_f32_16x16x32_bf16 v[104:107], v[190:193], v[218:221], v[104:107]
	v_mfma_f32_16x16x32_bf16 v[214:217], v[190:193], v[222:225], v[108:111]
	s_waitcnt lgkmcnt(4)
	v_mfma_f32_16x16x32_bf16 v[112:115], v[194:197], v[230:233], v[96:99]
	v_mfma_f32_16x16x32_bf16 v[108:111], v[194:197], v[234:237], v[100:103]
	s_waitcnt lgkmcnt(0)
	v_mfma_f32_16x16x32_bf16 v[104:107], v[194:197], v[242:245], v[104:107]
	v_mfma_f32_16x16x32_bf16 v[100:103], v[194:197], v[246:249], v[214:217]
	s_min_u32 s20, s44, 59
	s_waitcnt lgkmcnt(0)
	s_barrier
	s_waitcnt vmcnt(18)
	ds_write_b128 v168, v[72:75]
	s_waitcnt vmcnt(17)
	ds_write_b128 v168, v[80:83] offset:8704
	s_waitcnt vmcnt(16)
	ds_write_b128 v168, v[76:79] offset:17408
	s_waitcnt vmcnt(15)
	ds_write_b128 v168, v[84:87] offset:26112
	s_waitcnt vmcnt(14)
	ds_write_b128 v169, v[88:91] offset:34816
	v_add_u32_e32 v72, s34, v138
	s_add_i32 s34, s20, 4
	s_waitcnt vmcnt(13)
	s_cmp_lg_u32 s69, 0
	s_cbranch_scc1 .Lev_skip_b
	ds_write_b128 v72, v[92:95]
.Lev_skip_b:
	v_sub_u32_e64 v72, 59, s44 clamp
	s_and_b64 s[20:21], exec, s[38:39]
	v_readfirstlane_b32 s20, v72
	s_cselect_b32 s48, s34, s20
	v_add_u32_e32 v96, s61, v143
	s_lshl_b32 s34, s48, 13
	s_lshl_b32 s49, s48, 14
	ds_read_b128 v[222:225], v96
	s_add_u32 s20, s43, s49
	s_addc_u32 s21, s63, 0
	v_lshl_add_u64 v[76:77], s[20:21], 0, v[120:121]
	global_load_dwordx4 v[72:75], v120, s[20:21] nt
	v_add_co_u32_e64 v76, s[20:21], s60, v76
	s_waitcnt lgkmcnt(0)
	v_pk_mul_f32 v[118:119], v[118:119], v[224:225]
	v_addc_co_u32_e64 v77, s[20:21], 0, v77, s[20:21]
	v_pk_mul_f32 v[116:117], v[116:117], v[222:223]
	s_add_u32 s20, s64, s49
	v_pk_mul_f32 v[114:115], v[114:115], v[118:119]
	v_pk_mul_f32 v[112:113], v[112:113], v[116:117]
	s_addc_u32 s21, s65, 0
	v_add_u32_e32 v96, 0x1ea00, v185
	v_cvt_pk_bf16_f32 v222, v112, v113
	v_cvt_pk_bf16_f32 v223, v114, v115
	v_pk_mul_f32 v[110:111], v[110:111], v[118:119]
	v_pk_mul_f32 v[108:109], v[108:109], v[116:117]
	v_lshl_add_u64 v[84:85], s[20:21], 0, v[120:121]
	ds_read_b128 v[96:99], v96
	ds_write_b64 v182, v[222:223]
	v_cvt_pk_bf16_f32 v222, v108, v109
	v_cvt_pk_bf16_f32 v223, v110, v111
	v_pk_mul_f32 v[106:107], v[106:107], v[118:119]
	v_pk_mul_f32 v[104:105], v[104:105], v[116:117]
	v_pk_mul_f32 v[102:103], v[102:103], v[118:119]
	v_pk_mul_f32 v[100:101], v[100:101], v[116:117]
	global_load_dwordx4 v[80:83], v[76:77], off nt
	v_lshl_add_u64 v[88:89], v[146:147], 0, s[34:35]
	global_load_dwordx4 v[76:79], v120, s[20:21] nt
	v_add_co_u32_e64 v84, s[20:21], s60, v84
	s_lshl_b32 s34, s48, 10
	ds_write_b64 v182, v[222:223] offset:4352
	v_cvt_pk_bf16_f32 v222, v104, v105
	v_cvt_pk_bf16_f32 v223, v106, v107
	v_cvt_pk_bf16_f32 v116, v100, v101
	v_cvt_pk_bf16_f32 v117, v102, v103
	v_addc_co_u32_e64 v85, s[20:21], 0, v85, s[20:21]
	v_lshl_add_u64 v[92:93], v[148:149], 0, s[34:35]
	ds_write_b64 v182, v[222:223] offset:8704
	ds_write_b64 v182, v[116:117] offset:13056
	global_load_dwordx4 v[84:87], v[84:85], off nt
	global_load_dwordx4 v[88:91], v[88:89], off nt
	global_load_dwordx4 v[92:95], v[92:93], off
	s_waitcnt lgkmcnt(0)
	s_barrier
	ds_read_b128 v[218:221], v183
	ds_read_b128 v[230:233], v183 offset:64
	ds_read_b128 v[242:245], v183 offset:128
	s_add_i32 s34, s44, 1
	s_and_b64 s[20:21], exec, s[38:39]
	s_cselect_b32 s20, s34, s47
	s_lshl_b32 s34, s20, 6
	s_add_i32 s47, s47, -2
	v_lshl_add_u64 v[152:153], v[152:153], 0, s[36:37]
	s_waitcnt lgkmcnt(2)
	v_mfma_f32_16x16x32_bf16 v[198:201], v[218:221], v[122:125], 0
	v_mfma_f32_16x16x32_bf16 v[202:205], v[218:221], v[126:129], 0
	ds_read_b128 v[218:221], v183 offset:192
	s_waitcnt lgkmcnt(2)
	v_mfma_f32_16x16x32_bf16 v[198:201], v[230:233], v[130:133], v[198:201]
	v_mfma_f32_16x16x32_bf16 v[202:205], v[230:233], v[160:163], v[202:205]
	ds_read_b128 v[230:233], v170 offset:17408
	ds_read_b128 v[122:125], v171
	ds_read_b128 v[126:129], v172
	s_waitcnt lgkmcnt(4)
	v_mfma_f32_16x16x32_bf16 v[198:201], v[242:245], v[210:213], v[198:201]
	v_mfma_f32_16x16x32_bf16 v[202:205], v[242:245], v[154:157], v[202:205]
	ds_read_b128 v[242:245], v170 offset:17472
	ds_read_b128 v[130:133], v171 offset:64
	ds_read_b128 v[160:163], v172 offset:64
	s_waitcnt lgkmcnt(6)
	v_mfma_f32_16x16x32_bf16 v[198:201], v[218:221], v[206:209], v[198:201]
	v_mfma_f32_16x16x32_bf16 v[202:205], v[218:221], v[174:177], v[202:205]
	ds_read_b128 v[218:221], v170 offset:17536
	ds_read_b128 v[210:213], v171 offset:128
	ds_read_b128 v[154:157], v172 offset:128
	s_waitcnt lgkmcnt(6)
	v_mfma_f32_16x16x32_bf16 v[190:193], v[230:233], v[122:125], 0
	v_mfma_f32_16x16x32_bf16 v[194:197], v[230:233], v[126:129], 0
	ds_read_b128 v[230:233], v170 offset:17600
	ds_read_b128 v[206:209], v171 offset:192
	ds_read_b128 v[174:177], v172 offset:192
	s_waitcnt lgkmcnt(6)
	v_mfma_f32_16x16x32_bf16 v[190:193], v[242:245], v[130:133], v[190:193]
	v_mfma_f32_16x16x32_bf16 v[194:197], v[242:245], v[160:163], v[194:197]
	ds_read_b64_tr_b16 v[242:243], v139 offset:44032
	ds_read_b64_tr_b16 v[244:245], v139 offset:44544
	ds_read_b128 v[246:249], v142 offset:9216
	ds_read_b128 v[250:253], v159 offset:9216
	s_waitcnt lgkmcnt(7)
	v_mfma_f32_16x16x32_bf16 v[190:193], v[218:221], v[210:213], v[190:193]
	v_mfma_f32_16x16x32_bf16 v[194:197], v[218:221], v[154:157], v[194:197]
	ds_read_b64_tr_b16 v[218:219], v139 offset:48128
	ds_read_b64_tr_b16 v[220:221], v139 offset:48640
	ds_read_b128 v[222:225], v142 offset:9280
	ds_read_b128 v[226:229], v159 offset:9280
	s_waitcnt lgkmcnt(8)
	v_mfma_f32_16x16x32_bf16 v[190:193], v[230:233], v[206:209], v[190:193]
	v_mfma_f32_16x16x32_bf16 v[194:197], v[230:233], v[174:177], v[194:197]
	s_nop 6
	v_cndmask_b32_e32 v190, 0, v190, vcc
	v_cndmask_b32_e64 v191, 0, v191, s[6:7]
	v_cndmask_b32_e64 v192, 0, v192, s[8:9]
	v_cndmask_b32_e64 v193, 0, v193, s[10:11]
	v_cvt_pk_bf16_f32 v190, v190, v191
	v_cvt_pk_bf16_f32 v191, v192, v193
	v_cndmask_b32_e64 v194, 0, v194, s[12:13]
	v_cndmask_b32_e64 v195, 0, v195, s[14:15]
	v_cndmask_b32_e64 v196, 0, v196, s[16:17]
	v_cndmask_b32_e64 v197, 0, v197, s[18:19]
	v_cvt_pk_bf16_f32 v194, v194, v195
	v_cvt_pk_bf16_f32 v195, v196, v197
	ds_write_b64 v164, v[190:191]
	ds_write_b64 v180, v[194:195]
	ds_read_b64_tr_b16 v[190:191], v178 offset:61440
	ds_read_b64_tr_b16 v[192:193], v178 offset:62528
	ds_read_b64_tr_b16 v[194:195], v181 offset:8704
	ds_read_b64_tr_b16 v[196:197], v181 offset:9792
	s_waitcnt lgkmcnt(10)
	v_mfma_f32_16x16x32_bf16 v[198:201], v[242:245], v[246:249], v[198:201]
	v_mfma_f32_16x16x32_bf16 v[202:205], v[242:245], v[250:253], v[202:205]
	ds_read_b64_tr_b16 v[242:243], v186 offset:44032
	ds_read_b64_tr_b16 v[244:245], v186 offset:44544
	ds_read_b64_tr_b16 v[246:247], v187 offset:44032
	ds_read_b64_tr_b16 v[248:249], v187 offset:44544
	s_waitcnt lgkmcnt(10)
	v_mfma_f32_16x16x32_bf16 v[198:201], v[218:221], v[222:225], v[198:201]
	v_mfma_f32_16x16x32_bf16 v[202:205], v[218:221], v[226:229], v[202:205]
	ds_read_b64_tr_b16 v[218:219], v188 offset:44032
	ds_read_b64_tr_b16 v[220:221], v188 offset:44544
	ds_read_b64_tr_b16 v[222:223], v189 offset:44032
	ds_read_b64_tr_b16 v[224:225], v189 offset:44544
	s_waitcnt lgkmcnt(8)
	ds_read_b64_tr_b16 v[230:231], v186 offset:48128
	ds_read_b64_tr_b16 v[232:233], v186 offset:48640
	ds_read_b64_tr_b16 v[234:235], v187 offset:48128
	ds_read_b64_tr_b16 v[236:237], v187 offset:48640
	s_waitcnt lgkmcnt(8)
	v_mfma_f32_16x16x32_bf16 v[112:115], v[190:193], v[242:245], v[112:115]
	v_mfma_f32_16x16x32_bf16 v[108:111], v[190:193], v[246:249], v[108:111]
	ds_read_b64_tr_b16 v[242:243], v188 offset:48128
	ds_read_b64_tr_b16 v[244:245], v188 offset:48640
	ds_read_b64_tr_b16 v[246:247], v189 offset:48128
	ds_read_b64_tr_b16 v[248:249], v189 offset:48640
	v_cvt_pk_bf16_f32 v198, v198, v199
	v_cvt_pk_bf16_f32 v199, v200, v201
	v_cvt_pk_bf16_f32 v200, v202, v203
	v_cvt_pk_bf16_f32 v201, v204, v205
	v_add_u32_e32 v254, s34, v173
	v_mad_u64_u32 v[254:255], s[20:21], v254, s42, 0
	v_lshl_add_u64 v[254:255], v[254:255], 1, v[150:151]
	v_permlane16_swap_b32_e32 v198, v200
	v_permlane16_swap_b32_e32 v199, v201
	global_store_dwordx4 v[254:255], v[198:201], off
	s_waitcnt lgkmcnt(8)
	v_mfma_f32_16x16x32_bf16 v[214:217], v[190:193], v[218:221], v[104:107]
	v_mfma_f32_16x16x32_bf16 v[116:119], v[190:193], v[222:225], v[100:103]
	s_waitcnt lgkmcnt(4)
	v_mfma_f32_16x16x32_bf16 v[100:103], v[194:197], v[230:233], v[112:115]
	v_mfma_f32_16x16x32_bf16 v[104:107], v[194:197], v[234:237], v[108:111]
	s_waitcnt lgkmcnt(0)
	v_mfma_f32_16x16x32_bf16 v[108:111], v[194:197], v[242:245], v[214:217]
	v_mfma_f32_16x16x32_bf16 v[112:115], v[194:197], v[246:249], v[116:119]
	s_add_i32 s20, s44, 2
	s_cmp_lt_u32 s44, 62
	s_mov_b32 s44, s20
	s_waitcnt lgkmcnt(0)
	s_barrier
	s_cbranch_scc1 .LBB0_350
	s_add_i32 s30, s30, s28
	v_lshl_add_u64 v[140:141], v[140:141], 0, s[26:27]
	s_cmpk_lt_i32 s30, 0x100
	v_add_u32_e32 v165, s29, v165
	s_cbranch_scc1 .LBB0_344
